# attention unit: one static s_setprio 1 for waves 4-7 (the second-dispatched half) for the whole unit
# speedup vs baseline: 1.0031x; 1.0031x over previous
.Lam_go:
	s_bfe_u32 s14, s46, 0x10001
	s_lshl_b32 s15, s12, 9
	s_lshl_b32 s28, s14, 8
	s_add_i32 s28, s28, s15
	s_lshl_b32 s8, s10, 12
	s_add_i32 s8, s8, s28
	s_add_u32 s16, s40, s8
	s_addc_u32 s17, s41, 0
	s_lshl_b32 s8, s11, 12
	s_add_i32 s9, s8, s28
	s_add_u32 s18, s42, s9
	s_addc_u32 s19, s43, 0
	s_add_i32 s9, s8, s15
	s_add_u32 s20, s44, s9
	s_addc_u32 s21, s45, 0
	s_lshl_b32 s8, s10, 13
	s_lshl_b32 s9, s28, 1
	s_add_i32 s8, s8, s9
	s_add_u32 s22, s48, s8
	s_addc_u32 s23, s49, 0
	v_mbcnt_lo_u32_b32 v96, -1, 0
	v_mbcnt_hi_u32_b32 v96, -1, v96
	s_lshr_b32 s36, s84, 6
	s_cmp_lt_u32 s36, 4
	s_cbranch_scc1 .Lam_prio
	s_setprio 1
.Lam_prio:
	s_lshl_b32 s38, s36, 3
	s_lshl_b32 s39, s36, 11
	s_lshl_b32 s47, s36, 12
	s_add_i32 s47, s47, 0x4000
	s_lshl_b32 s50, s36, 8
	s_add_i32 s50, s50, 0x18000
	v_and_b32_e32 v240, 31, v96
	v_lshrrev_b32_e32 v241, 5, v96
	s_lshl_b32 s37, s36, 5
	v_add_u32_e32 v242, s37, v240
	v_lshlrev_b32_e32 v242, 12, v242
	v_lshl_add_u32 v242, v241, 4, v242
	global_load_dwordx4 v[130:133], v242, s[16:17]
	global_load_dwordx4 v[134:137], v242, s[16:17] offset:32
	global_load_dwordx4 v[138:141], v242, s[16:17] offset:64
	global_load_dwordx4 v[142:145], v242, s[16:17] offset:96
	global_load_dwordx4 v[146:149], v242, s[16:17] offset:128
	global_load_dwordx4 v[150:153], v242, s[16:17] offset:160
	global_load_dwordx4 v[154:157], v242, s[16:17] offset:192
	global_load_dwordx4 v[158:161], v242, s[16:17] offset:224
	v_lshlrev_b32_e32 v243, 8, v240
	v_and_b32_e32 v238, 7, v240
	v_lshlrev_b32_e32 v238, 4, v238
	v_lshlrev_b32_e32 v239, 4, v241
	v_mov_b32_e32 v228, v239
	v_xor_b32_e32 v228, v228, v238
	v_add_u32_e32 v228, v228, v243
	v_or_b32_e32 v229, 32, v239
	v_xor_b32_e32 v229, v229, v238
	v_add_u32_e32 v229, v229, v243
	v_or_b32_e32 v230, 64, v239
	v_xor_b32_e32 v230, v230, v238
	v_add_u32_e32 v230, v230, v243
	v_or_b32_e32 v231, 96, v239
	v_xor_b32_e32 v231, v231, v238
	v_add_u32_e32 v231, v231, v243
	v_or_b32_e32 v232, 128, v239
	v_xor_b32_e32 v232, v232, v238
	v_add_u32_e32 v232, v232, v243
	v_or_b32_e32 v233, 160, v239
	v_xor_b32_e32 v233, v233, v238
	v_add_u32_e32 v233, v233, v243
	v_or_b32_e32 v234, 192, v239
	v_xor_b32_e32 v234, v234, v238
	v_add_u32_e32 v234, v234, v243
	v_or_b32_e32 v235, 224, v239
	v_xor_b32_e32 v235, v235, v238
	v_add_u32_e32 v235, v235, v243
	v_and_b32_e32 v238, 3, v96
	v_lshlrev_b32_e32 v236, 3, v238
	v_bfe_u32 v238, v96, 2, 2
	v_lshl_or_b32 v236, v238, 6, v236
	v_bfe_u32 v238, v96, 4, 1
	v_lshl_or_b32 v236, v238, 5, v236
	v_lshl_or_b32 v236, v241, 8, v236
	v_add_u32_e32 v237, 0x10000, v236
	v_add_u32_e32 v236, 0x4000, v236
	v_lshrrev_b32_e32 v238, 4, v96
	v_and_b32_e32 v239, 15, v96
	v_add_u32_e32 v243, 0, v238
	v_xor_b32_e32 v244, v239, v243
	v_lshlrev_b32_e32 v244, 4, v244
	v_add_u32_e32 v243, s38, v243
	v_lshl_add_u32 v244, v243, 12, v244
	v_add_u32_e32 v243, 4, v238
	v_xor_b32_e32 v245, v239, v243
	v_lshlrev_b32_e32 v245, 4, v245
	v_add_u32_e32 v243, s38, v243
	v_lshl_add_u32 v245, v243, 12, v245
	v_lshrrev_b32_e32 v238, 2, v240
	v_add_u32_e32 v238, s38, v238
	v_and_b32_e32 v239, 0xfffffff3, v238
	v_and_b32_e32 v243, 4, v238
	v_lshl_or_b32 v239, v243, 1, v239
	v_and_b32_e32 v243, 8, v238
	v_lshrrev_b32_e32 v243, 1, v243
	v_or_b32_e32 v239, v239, v243
	v_lshlrev_b32_e32 v239, 12, v239
	v_and_b32_e32 v238, 3, v240
	v_lshlrev_b32_e32 v238, 4, v238
	v_add_u32_e32 v243, 0, v241
	v_lshl_add_u32 v243, v243, 6, v238
	v_add_u32_e32 v246, v239, v243
	v_add_u32_e32 v243, 2, v241
	v_lshl_add_u32 v243, v243, 6, v238
	v_add_u32_e32 v247, v239, v243
	v_add_u32_e32 v243, 4, v241
	v_lshl_add_u32 v243, v243, 6, v238
	v_add_u32_e32 v248, v239, v243
	v_add_u32_e32 v243, 6, v241
	v_lshl_add_u32 v243, v243, 6, v238
	v_add_u32_e32 v249, v239, v243
	v_mov_b32_e32 v238, 0xf149f2ca
	v_mov_b32_e32 v239, 0
	v_mov_b32_e32 v0, 0
	v_mov_b32_e32 v1, 0
	v_mov_b32_e32 v2, 0
	v_mov_b32_e32 v3, 0
	v_mov_b32_e32 v4, 0
	v_mov_b32_e32 v5, 0
	v_mov_b32_e32 v6, 0
	v_mov_b32_e32 v7, 0
	v_mov_b32_e32 v8, 0
	v_mov_b32_e32 v9, 0
	v_mov_b32_e32 v10, 0
	v_mov_b32_e32 v11, 0
	v_mov_b32_e32 v12, 0
	v_mov_b32_e32 v13, 0
	v_mov_b32_e32 v14, 0
	v_mov_b32_e32 v15, 0
	v_mov_b32_e32 v16, 0
	v_mov_b32_e32 v17, 0
	v_mov_b32_e32 v18, 0
	v_mov_b32_e32 v19, 0
	v_mov_b32_e32 v20, 0
	v_mov_b32_e32 v21, 0
	v_mov_b32_e32 v22, 0
	v_mov_b32_e32 v23, 0
	v_mov_b32_e32 v24, 0
	v_mov_b32_e32 v25, 0
	v_mov_b32_e32 v26, 0
	v_mov_b32_e32 v27, 0
	v_mov_b32_e32 v28, 0
	v_mov_b32_e32 v29, 0
	v_mov_b32_e32 v30, 0
	v_mov_b32_e32 v31, 0
	v_mov_b32_e32 v32, 0
	v_mov_b32_e32 v33, 0
	v_mov_b32_e32 v34, 0
	v_mov_b32_e32 v35, 0
	v_mov_b32_e32 v36, 0
	v_mov_b32_e32 v37, 0
	v_mov_b32_e32 v38, 0
	v_mov_b32_e32 v39, 0
	v_mov_b32_e32 v40, 0
	v_mov_b32_e32 v41, 0
	v_mov_b32_e32 v42, 0
	v_mov_b32_e32 v43, 0
	v_mov_b32_e32 v44, 0
	v_mov_b32_e32 v45, 0
	v_mov_b32_e32 v46, 0
	v_mov_b32_e32 v47, 0
	v_mov_b32_e32 v48, 0
	v_mov_b32_e32 v49, 0
	v_mov_b32_e32 v50, 0
	v_mov_b32_e32 v51, 0
	v_mov_b32_e32 v52, 0
	v_mov_b32_e32 v53, 0
	v_mov_b32_e32 v54, 0
	v_mov_b32_e32 v55, 0
	v_mov_b32_e32 v56, 0
	v_mov_b32_e32 v57, 0
	v_mov_b32_e32 v58, 0
	v_mov_b32_e32 v59, 0
	v_mov_b32_e32 v60, 0
	v_mov_b32_e32 v61, 0
	v_mov_b32_e32 v62, 0
	v_mov_b32_e32 v63, 0
	v_mov_b32_e32 v64, 0
	v_mov_b32_e32 v65, 0
	v_mov_b32_e32 v66, 0
	v_mov_b32_e32 v67, 0
	v_mov_b32_e32 v68, 0
	v_mov_b32_e32 v69, 0
	v_mov_b32_e32 v70, 0
	v_mov_b32_e32 v71, 0
	v_mov_b32_e32 v72, 0
	v_mov_b32_e32 v73, 0
	v_mov_b32_e32 v74, 0
	v_mov_b32_e32 v75, 0
	v_mov_b32_e32 v76, 0
	v_mov_b32_e32 v77, 0
	v_mov_b32_e32 v78, 0
	v_mov_b32_e32 v79, 0
	v_mov_b32_e32 v80, 0
	v_mov_b32_e32 v81, 0
	v_mov_b32_e32 v82, 0
	v_mov_b32_e32 v83, 0
	v_mov_b32_e32 v84, 0
	v_mov_b32_e32 v85, 0
	v_mov_b32_e32 v86, 0
	v_mov_b32_e32 v87, 0
	v_mov_b32_e32 v88, 0
	v_mov_b32_e32 v89, 0
	v_mov_b32_e32 v90, 0
	v_mov_b32_e32 v91, 0
	v_mov_b32_e32 v92, 0
	v_mov_b32_e32 v93, 0
	v_mov_b32_e32 v94, 0
	v_mov_b32_e32 v95, 0
	v_mov_b32_e32 v98, 0
	v_mov_b32_e32 v99, 0
	v_mov_b32_e32 v100, 0
	v_mov_b32_e32 v101, 0
	v_mov_b32_e32 v102, 0
	v_mov_b32_e32 v103, 0
	v_mov_b32_e32 v104, 0
	v_mov_b32_e32 v105, 0
	v_mov_b32_e32 v106, 0
	v_mov_b32_e32 v107, 0
	v_mov_b32_e32 v108, 0
	v_mov_b32_e32 v109, 0
	v_mov_b32_e32 v110, 0
	v_mov_b32_e32 v111, 0
	v_mov_b32_e32 v112, 0
	v_mov_b32_e32 v113, 0
	v_mov_b32_e32 v114, 0
	v_mov_b32_e32 v115, 0
	v_mov_b32_e32 v116, 0
	v_mov_b32_e32 v117, 0
	v_mov_b32_e32 v118, 0
	v_mov_b32_e32 v119, 0
	v_mov_b32_e32 v120, 0
	v_mov_b32_e32 v121, 0
	v_mov_b32_e32 v122, 0
	v_mov_b32_e32 v123, 0
	v_mov_b32_e32 v124, 0
	v_mov_b32_e32 v125, 0
	v_mov_b32_e32 v126, 0
	v_mov_b32_e32 v127, 0
	v_mov_b32_e32 v128, 0
	v_mov_b32_e32 v129, 0
	s_add_i32 m0, s39, 0x0
	s_nop 0
	global_load_lds_dwordx4 v244, s[18:19]
	s_add_i32 m0, s39, 0x400
	s_nop 0
	global_load_lds_dwordx4 v245, s[18:19]
	s_add_i32 m0, s47, 0x0
	s_nop 0
	global_load_lds_dwordx4 v246, s[20:21]
	s_add_i32 m0, s47, 0x400
	s_nop 0
	global_load_lds_dwordx4 v247, s[20:21]
	s_add_i32 m0, s47, 0x800
	s_nop 0
	global_load_lds_dwordx4 v248, s[20:21]
	s_add_i32 m0, s47, 0xc00
	s_nop 0
	global_load_lds_dwordx4 v249, s[20:21]
	s_add_u32 s18, s18, 0x40000
	s_addc_u32 s19, s19, 0
	s_add_u32 s20, s20, 0x40000
	s_addc_u32 s21, s21, 0
	s_add_i32 m0, s39, 0xc000
	s_nop 0
	global_load_lds_dwordx4 v244, s[18:19]
	s_add_i32 m0, s39, 0xc400
	s_nop 0
	global_load_lds_dwordx4 v245, s[18:19]
	s_add_i32 m0, s47, 0xc000
	s_nop 0
	global_load_lds_dwordx4 v246, s[20:21]
	s_add_i32 m0, s47, 0xc400
	s_nop 0
	global_load_lds_dwordx4 v247, s[20:21]
	s_add_i32 m0, s47, 0xc800
	s_nop 0
	global_load_lds_dwordx4 v248, s[20:21]
	s_add_i32 m0, s47, 0xcc00
	s_nop 0
	global_load_lds_dwordx4 v249, s[20:21]
	s_add_u32 s18, s18, 0x40000
	s_addc_u32 s19, s19, 0
	s_add_u32 s20, s20, 0x40000
	s_addc_u32 s21, s21, 0
	s_waitcnt vmcnt(0)
	s_barrier

.Lam_pfx:
	s_mov_b64 exec, s[8:9]
	v_writelane_b32 v251, 1, 20
	v_and_b32_e32 v240, 31, v96
	v_lshl_add_u32 v241, v240, 2, s50
	ds_write_b32 v241, v239 offset:128
	v_lshrrev_b32_e32 v241, 5, v96
	v_lshl_add_u32 v242, v241, 4, s50
	s_waitcnt lgkmcnt(0)
	ds_read_b128 v[212:215], v242 offset:128
	ds_read_b128 v[216:219], v242 offset:160
	ds_read_b128 v[220:223], v242 offset:192
	ds_read_b128 v[224:227], v242 offset:224
	s_lshl_b32 s37, s36, 5
	v_lshl_add_u32 v241, v241, 2, s37
	v_lshlrev_b32_e32 v241, 13, v241
	v_lshl_add_u32 v241, v240, 1, v241
	s_waitcnt lgkmcnt(0)
	v_rcp_f32_e32 v212, v212
	v_rcp_f32_e32 v213, v213
	v_rcp_f32_e32 v214, v214
	v_rcp_f32_e32 v215, v215
	v_rcp_f32_e32 v216, v216
	v_rcp_f32_e32 v217, v217
	v_rcp_f32_e32 v218, v218
	v_rcp_f32_e32 v219, v219
	v_rcp_f32_e32 v220, v220
	v_rcp_f32_e32 v221, v221
	v_rcp_f32_e32 v222, v222
	v_rcp_f32_e32 v223, v223
	v_rcp_f32_e32 v224, v224
	v_rcp_f32_e32 v225, v225
	v_rcp_f32_e32 v226, v226
	v_rcp_f32_e32 v227, v227
	s_nop 0
	v_mov_b32_e32 v240, v241
	v_mul_f32_e32 v162, v0, v212
	v_cvt_pk_bf16_f32 v162, v162, v162
	global_store_short v240, v162, s[22:23]
	v_mul_f32_e32 v163, v16, v212
	v_cvt_pk_bf16_f32 v163, v163, v163
	global_store_short v240, v163, s[22:23] offset:64
	v_mul_f32_e32 v164, v32, v212
	v_cvt_pk_bf16_f32 v164, v164, v164
	global_store_short v240, v164, s[22:23] offset:128
	v_mul_f32_e32 v165, v48, v212
	v_cvt_pk_bf16_f32 v165, v165, v165
	global_store_short v240, v165, s[22:23] offset:192
	v_mul_f32_e32 v166, v64, v212
	v_cvt_pk_bf16_f32 v166, v166, v166
	global_store_short v240, v166, s[22:23] offset:256
	v_mul_f32_e32 v167, v80, v212
	v_cvt_pk_bf16_f32 v167, v167, v167
	global_store_short v240, v167, s[22:23] offset:320
	v_mul_f32_e32 v168, v98, v212
	v_cvt_pk_bf16_f32 v168, v168, v168
	global_store_short v240, v168, s[22:23] offset:384
	v_mul_f32_e32 v169, v114, v212
	v_cvt_pk_bf16_f32 v169, v169, v169
	global_store_short v240, v169, s[22:23] offset:448
	v_add_u32_e32 v240, 0x2000, v241
	v_mul_f32_e32 v170, v1, v213
	v_cvt_pk_bf16_f32 v170, v170, v170
	global_store_short v240, v170, s[22:23]
	v_mul_f32_e32 v171, v17, v213
	v_cvt_pk_bf16_f32 v171, v171, v171
	global_store_short v240, v171, s[22:23] offset:64
	v_mul_f32_e32 v172, v33, v213
	v_cvt_pk_bf16_f32 v172, v172, v172
	global_store_short v240, v172, s[22:23] offset:128
	v_mul_f32_e32 v173, v49, v213
	v_cvt_pk_bf16_f32 v173, v173, v173
	global_store_short v240, v173, s[22:23] offset:192
	v_mul_f32_e32 v174, v65, v213
	v_cvt_pk_bf16_f32 v174, v174, v174
	global_store_short v240, v174, s[22:23] offset:256
	v_mul_f32_e32 v175, v81, v213
	v_cvt_pk_bf16_f32 v175, v175, v175
	global_store_short v240, v175, s[22:23] offset:320
	v_mul_f32_e32 v176, v99, v213
	v_cvt_pk_bf16_f32 v176, v176, v176
	global_store_short v240, v176, s[22:23] offset:384
	v_mul_f32_e32 v177, v115, v213
	v_cvt_pk_bf16_f32 v177, v177, v177
	global_store_short v240, v177, s[22:23] offset:448
	v_add_u32_e32 v240, 0x4000, v241
	v_mul_f32_e32 v178, v2, v214
	v_cvt_pk_bf16_f32 v178, v178, v178
	global_store_short v240, v178, s[22:23]
	v_mul_f32_e32 v179, v18, v214
	v_cvt_pk_bf16_f32 v179, v179, v179
	global_store_short v240, v179, s[22:23] offset:64
	v_mul_f32_e32 v180, v34, v214
	v_cvt_pk_bf16_f32 v180, v180, v180
	global_store_short v240, v180, s[22:23] offset:128
	v_mul_f32_e32 v181, v50, v214
	v_cvt_pk_bf16_f32 v181, v181, v181
	global_store_short v240, v181, s[22:23] offset:192
	v_mul_f32_e32 v182, v66, v214
	v_cvt_pk_bf16_f32 v182, v182, v182
	global_store_short v240, v182, s[22:23] offset:256
	v_mul_f32_e32 v183, v82, v214
	v_cvt_pk_bf16_f32 v183, v183, v183
	global_store_short v240, v183, s[22:23] offset:320
	v_mul_f32_e32 v184, v100, v214
	v_cvt_pk_bf16_f32 v184, v184, v184
	global_store_short v240, v184, s[22:23] offset:384
	v_mul_f32_e32 v185, v116, v214
	v_cvt_pk_bf16_f32 v185, v185, v185
	global_store_short v240, v185, s[22:23] offset:448
	v_add_u32_e32 v240, 0x6000, v241
	v_mul_f32_e32 v186, v3, v215
	v_cvt_pk_bf16_f32 v186, v186, v186
	global_store_short v240, v186, s[22:23]
	v_mul_f32_e32 v187, v19, v215
	v_cvt_pk_bf16_f32 v187, v187, v187
	global_store_short v240, v187, s[22:23] offset:64
	v_mul_f32_e32 v188, v35, v215
	v_cvt_pk_bf16_f32 v188, v188, v188
	global_store_short v240, v188, s[22:23] offset:128
	v_mul_f32_e32 v189, v51, v215
	v_cvt_pk_bf16_f32 v189, v189, v189
	global_store_short v240, v189, s[22:23] offset:192
	v_mul_f32_e32 v190, v67, v215
	v_cvt_pk_bf16_f32 v190, v190, v190
	global_store_short v240, v190, s[22:23] offset:256
	v_mul_f32_e32 v191, v83, v215
	v_cvt_pk_bf16_f32 v191, v191, v191
	global_store_short v240, v191, s[22:23] offset:320
	v_mul_f32_e32 v192, v101, v215
	v_cvt_pk_bf16_f32 v192, v192, v192
	global_store_short v240, v192, s[22:23] offset:384
	v_mul_f32_e32 v193, v117, v215
	v_cvt_pk_bf16_f32 v193, v193, v193
	global_store_short v240, v193, s[22:23] offset:448
	v_add_u32_e32 v240, 0x10000, v241
	v_mul_f32_e32 v162, v4, v216
	v_cvt_pk_bf16_f32 v162, v162, v162
	global_store_short v240, v162, s[22:23]
	v_mul_f32_e32 v163, v20, v216
	v_cvt_pk_bf16_f32 v163, v163, v163
	global_store_short v240, v163, s[22:23] offset:64
	v_mul_f32_e32 v164, v36, v216
	v_cvt_pk_bf16_f32 v164, v164, v164
	global_store_short v240, v164, s[22:23] offset:128
	v_mul_f32_e32 v165, v52, v216
	v_cvt_pk_bf16_f32 v165, v165, v165
	global_store_short v240, v165, s[22:23] offset:192
	v_mul_f32_e32 v166, v68, v216
	v_cvt_pk_bf16_f32 v166, v166, v166
	global_store_short v240, v166, s[22:23] offset:256
	v_mul_f32_e32 v167, v84, v216
	v_cvt_pk_bf16_f32 v167, v167, v167
	global_store_short v240, v167, s[22:23] offset:320
	v_mul_f32_e32 v168, v102, v216
	v_cvt_pk_bf16_f32 v168, v168, v168
	global_store_short v240, v168, s[22:23] offset:384
	v_mul_f32_e32 v169, v118, v216
	v_cvt_pk_bf16_f32 v169, v169, v169
	global_store_short v240, v169, s[22:23] offset:448
	v_add_u32_e32 v240, 0x12000, v241
	v_mul_f32_e32 v170, v5, v217
	v_cvt_pk_bf16_f32 v170, v170, v170
	global_store_short v240, v170, s[22:23]
	v_mul_f32_e32 v171, v21, v217
	v_cvt_pk_bf16_f32 v171, v171, v171
	global_store_short v240, v171, s[22:23] offset:64
	v_mul_f32_e32 v172, v37, v217
	v_cvt_pk_bf16_f32 v172, v172, v172
	global_store_short v240, v172, s[22:23] offset:128
	v_mul_f32_e32 v173, v53, v217
	v_cvt_pk_bf16_f32 v173, v173, v173
	global_store_short v240, v173, s[22:23] offset:192
	v_mul_f32_e32 v174, v69, v217
	v_cvt_pk_bf16_f32 v174, v174, v174
	global_store_short v240, v174, s[22:23] offset:256
	v_mul_f32_e32 v175, v85, v217
	v_cvt_pk_bf16_f32 v175, v175, v175
	global_store_short v240, v175, s[22:23] offset:320
	v_mul_f32_e32 v176, v103, v217
	v_cvt_pk_bf16_f32 v176, v176, v176
	global_store_short v240, v176, s[22:23] offset:384
	v_mul_f32_e32 v177, v119, v217
	v_cvt_pk_bf16_f32 v177, v177, v177
	global_store_short v240, v177, s[22:23] offset:448
	v_add_u32_e32 v240, 0x14000, v241
	v_mul_f32_e32 v178, v6, v218
	v_cvt_pk_bf16_f32 v178, v178, v178
	global_store_short v240, v178, s[22:23]
	v_mul_f32_e32 v179, v22, v218
	v_cvt_pk_bf16_f32 v179, v179, v179
	global_store_short v240, v179, s[22:23] offset:64
	v_mul_f32_e32 v180, v38, v218
	v_cvt_pk_bf16_f32 v180, v180, v180
	global_store_short v240, v180, s[22:23] offset:128
	v_mul_f32_e32 v181, v54, v218
	v_cvt_pk_bf16_f32 v181, v181, v181
	global_store_short v240, v181, s[22:23] offset:192
	v_mul_f32_e32 v182, v70, v218
	v_cvt_pk_bf16_f32 v182, v182, v182
	global_store_short v240, v182, s[22:23] offset:256
	v_mul_f32_e32 v183, v86, v218
	v_cvt_pk_bf16_f32 v183, v183, v183
	global_store_short v240, v183, s[22:23] offset:320
	v_mul_f32_e32 v184, v104, v218
	v_cvt_pk_bf16_f32 v184, v184, v184
	global_store_short v240, v184, s[22:23] offset:384
	v_mul_f32_e32 v185, v120, v218
	v_cvt_pk_bf16_f32 v185, v185, v185
	global_store_short v240, v185, s[22:23] offset:448
	v_add_u32_e32 v240, 0x16000, v241
	v_mul_f32_e32 v186, v7, v219
	v_cvt_pk_bf16_f32 v186, v186, v186
	global_store_short v240, v186, s[22:23]
	v_mul_f32_e32 v187, v23, v219
	v_cvt_pk_bf16_f32 v187, v187, v187
	global_store_short v240, v187, s[22:23] offset:64
	v_mul_f32_e32 v188, v39, v219
	v_cvt_pk_bf16_f32 v188, v188, v188
	global_store_short v240, v188, s[22:23] offset:128
	v_mul_f32_e32 v189, v55, v219
	v_cvt_pk_bf16_f32 v189, v189, v189
	global_store_short v240, v189, s[22:23] offset:192
	v_mul_f32_e32 v190, v71, v219
	v_cvt_pk_bf16_f32 v190, v190, v190
	global_store_short v240, v190, s[22:23] offset:256
	v_mul_f32_e32 v191, v87, v219
	v_cvt_pk_bf16_f32 v191, v191, v191
	global_store_short v240, v191, s[22:23] offset:320
	v_mul_f32_e32 v192, v105, v219
	v_cvt_pk_bf16_f32 v192, v192, v192
	global_store_short v240, v192, s[22:23] offset:384
	v_mul_f32_e32 v193, v121, v219
	v_cvt_pk_bf16_f32 v193, v193, v193
	global_store_short v240, v193, s[22:23] offset:448
	v_add_u32_e32 v240, 0x20000, v241
	v_mul_f32_e32 v162, v8, v220
	v_cvt_pk_bf16_f32 v162, v162, v162
	global_store_short v240, v162, s[22:23]
	v_mul_f32_e32 v163, v24, v220
	v_cvt_pk_bf16_f32 v163, v163, v163
	global_store_short v240, v163, s[22:23] offset:64
	v_mul_f32_e32 v164, v40, v220
	v_cvt_pk_bf16_f32 v164, v164, v164
	global_store_short v240, v164, s[22:23] offset:128
	v_mul_f32_e32 v165, v56, v220
	v_cvt_pk_bf16_f32 v165, v165, v165
	global_store_short v240, v165, s[22:23] offset:192
	v_mul_f32_e32 v166, v72, v220
	v_cvt_pk_bf16_f32 v166, v166, v166
	global_store_short v240, v166, s[22:23] offset:256
	v_mul_f32_e32 v167, v88, v220
	v_cvt_pk_bf16_f32 v167, v167, v167
	global_store_short v240, v167, s[22:23] offset:320
	v_mul_f32_e32 v168, v106, v220
	v_cvt_pk_bf16_f32 v168, v168, v168
	global_store_short v240, v168, s[22:23] offset:384
	v_mul_f32_e32 v169, v122, v220
	v_cvt_pk_bf16_f32 v169, v169, v169
	global_store_short v240, v169, s[22:23] offset:448
	v_add_u32_e32 v240, 0x22000, v241
	v_mul_f32_e32 v170, v9, v221
	v_cvt_pk_bf16_f32 v170, v170, v170
	global_store_short v240, v170, s[22:23]
	v_mul_f32_e32 v171, v25, v221
	v_cvt_pk_bf16_f32 v171, v171, v171
	global_store_short v240, v171, s[22:23] offset:64
	v_mul_f32_e32 v172, v41, v221
	v_cvt_pk_bf16_f32 v172, v172, v172
	global_store_short v240, v172, s[22:23] offset:128
	v_mul_f32_e32 v173, v57, v221
	v_cvt_pk_bf16_f32 v173, v173, v173
	global_store_short v240, v173, s[22:23] offset:192
	v_mul_f32_e32 v174, v73, v221
	v_cvt_pk_bf16_f32 v174, v174, v174
	global_store_short v240, v174, s[22:23] offset:256
	v_mul_f32_e32 v175, v89, v221
	v_cvt_pk_bf16_f32 v175, v175, v175
	global_store_short v240, v175, s[22:23] offset:320
	v_mul_f32_e32 v176, v107, v221
	v_cvt_pk_bf16_f32 v176, v176, v176
	global_store_short v240, v176, s[22:23] offset:384
	v_mul_f32_e32 v177, v123, v221
	v_cvt_pk_bf16_f32 v177, v177, v177
	global_store_short v240, v177, s[22:23] offset:448
	v_add_u32_e32 v240, 0x24000, v241
	v_mul_f32_e32 v178, v10, v222
	v_cvt_pk_bf16_f32 v178, v178, v178
	global_store_short v240, v178, s[22:23]
	v_mul_f32_e32 v179, v26, v222
	v_cvt_pk_bf16_f32 v179, v179, v179
	global_store_short v240, v179, s[22:23] offset:64
	v_mul_f32_e32 v180, v42, v222
	v_cvt_pk_bf16_f32 v180, v180, v180
	global_store_short v240, v180, s[22:23] offset:128
	v_mul_f32_e32 v181, v58, v222
	v_cvt_pk_bf16_f32 v181, v181, v181
	global_store_short v240, v181, s[22:23] offset:192
	v_mul_f32_e32 v182, v74, v222
	v_cvt_pk_bf16_f32 v182, v182, v182
	global_store_short v240, v182, s[22:23] offset:256
	v_mul_f32_e32 v183, v90, v222
	v_cvt_pk_bf16_f32 v183, v183, v183
	global_store_short v240, v183, s[22:23] offset:320
	v_mul_f32_e32 v184, v108, v222
	v_cvt_pk_bf16_f32 v184, v184, v184
	global_store_short v240, v184, s[22:23] offset:384
	v_mul_f32_e32 v185, v124, v222
	v_cvt_pk_bf16_f32 v185, v185, v185
	global_store_short v240, v185, s[22:23] offset:448
	v_add_u32_e32 v240, 0x26000, v241
	v_mul_f32_e32 v186, v11, v223
	v_cvt_pk_bf16_f32 v186, v186, v186
	global_store_short v240, v186, s[22:23]
	v_mul_f32_e32 v187, v27, v223
	v_cvt_pk_bf16_f32 v187, v187, v187
	global_store_short v240, v187, s[22:23] offset:64
	v_mul_f32_e32 v188, v43, v223
	v_cvt_pk_bf16_f32 v188, v188, v188
	global_store_short v240, v188, s[22:23] offset:128
	v_mul_f32_e32 v189, v59, v223
	v_cvt_pk_bf16_f32 v189, v189, v189
	global_store_short v240, v189, s[22:23] offset:192
	v_mul_f32_e32 v190, v75, v223
	v_cvt_pk_bf16_f32 v190, v190, v190
	global_store_short v240, v190, s[22:23] offset:256
	v_mul_f32_e32 v191, v91, v223
	v_cvt_pk_bf16_f32 v191, v191, v191
	global_store_short v240, v191, s[22:23] offset:320
	v_mul_f32_e32 v192, v109, v223
	v_cvt_pk_bf16_f32 v192, v192, v192
	global_store_short v240, v192, s[22:23] offset:384
	v_mul_f32_e32 v193, v125, v223
	v_cvt_pk_bf16_f32 v193, v193, v193
	global_store_short v240, v193, s[22:23] offset:448
	v_add_u32_e32 v240, 0x30000, v241
	v_mul_f32_e32 v162, v12, v224
	v_cvt_pk_bf16_f32 v162, v162, v162
	global_store_short v240, v162, s[22:23]
	v_mul_f32_e32 v163, v28, v224
	v_cvt_pk_bf16_f32 v163, v163, v163
	global_store_short v240, v163, s[22:23] offset:64
	v_mul_f32_e32 v164, v44, v224
	v_cvt_pk_bf16_f32 v164, v164, v164
	global_store_short v240, v164, s[22:23] offset:128
	v_mul_f32_e32 v165, v60, v224
	v_cvt_pk_bf16_f32 v165, v165, v165
	global_store_short v240, v165, s[22:23] offset:192
	v_mul_f32_e32 v166, v76, v224
	v_cvt_pk_bf16_f32 v166, v166, v166
	global_store_short v240, v166, s[22:23] offset:256
	v_mul_f32_e32 v167, v92, v224
	v_cvt_pk_bf16_f32 v167, v167, v167
	global_store_short v240, v167, s[22:23] offset:320
	v_mul_f32_e32 v168, v110, v224
	v_cvt_pk_bf16_f32 v168, v168, v168
	global_store_short v240, v168, s[22:23] offset:384
	v_mul_f32_e32 v169, v126, v224
	v_cvt_pk_bf16_f32 v169, v169, v169
	global_store_short v240, v169, s[22:23] offset:448
	v_add_u32_e32 v240, 0x32000, v241
	v_mul_f32_e32 v170, v13, v225
	v_cvt_pk_bf16_f32 v170, v170, v170
	global_store_short v240, v170, s[22:23]
	v_mul_f32_e32 v171, v29, v225
	v_cvt_pk_bf16_f32 v171, v171, v171
	global_store_short v240, v171, s[22:23] offset:64
	v_mul_f32_e32 v172, v45, v225
	v_cvt_pk_bf16_f32 v172, v172, v172
	global_store_short v240, v172, s[22:23] offset:128
	v_mul_f32_e32 v173, v61, v225
	v_cvt_pk_bf16_f32 v173, v173, v173
	global_store_short v240, v173, s[22:23] offset:192
	v_mul_f32_e32 v174, v77, v225
	v_cvt_pk_bf16_f32 v174, v174, v174
	global_store_short v240, v174, s[22:23] offset:256
	v_mul_f32_e32 v175, v93, v225
	v_cvt_pk_bf16_f32 v175, v175, v175
	global_store_short v240, v175, s[22:23] offset:320
	v_mul_f32_e32 v176, v111, v225
	v_cvt_pk_bf16_f32 v176, v176, v176
	global_store_short v240, v176, s[22:23] offset:384
	v_mul_f32_e32 v177, v127, v225
	v_cvt_pk_bf16_f32 v177, v177, v177
	global_store_short v240, v177, s[22:23] offset:448
	v_add_u32_e32 v240, 0x34000, v241
	v_mul_f32_e32 v178, v14, v226
	v_cvt_pk_bf16_f32 v178, v178, v178
	global_store_short v240, v178, s[22:23]
	v_mul_f32_e32 v179, v30, v226
	v_cvt_pk_bf16_f32 v179, v179, v179
	global_store_short v240, v179, s[22:23] offset:64
	v_mul_f32_e32 v180, v46, v226
	v_cvt_pk_bf16_f32 v180, v180, v180
	global_store_short v240, v180, s[22:23] offset:128
	v_mul_f32_e32 v181, v62, v226
	v_cvt_pk_bf16_f32 v181, v181, v181
	global_store_short v240, v181, s[22:23] offset:192
	v_mul_f32_e32 v182, v78, v226
	v_cvt_pk_bf16_f32 v182, v182, v182
	global_store_short v240, v182, s[22:23] offset:256
	v_mul_f32_e32 v183, v94, v226
	v_cvt_pk_bf16_f32 v183, v183, v183
	global_store_short v240, v183, s[22:23] offset:320
	v_mul_f32_e32 v184, v112, v226
	v_cvt_pk_bf16_f32 v184, v184, v184
	global_store_short v240, v184, s[22:23] offset:384
	v_mul_f32_e32 v185, v128, v226
	v_cvt_pk_bf16_f32 v185, v185, v185
	global_store_short v240, v185, s[22:23] offset:448
	v_add_u32_e32 v240, 0x36000, v241
	v_mul_f32_e32 v186, v15, v227
	v_cvt_pk_bf16_f32 v186, v186, v186
	global_store_short v240, v186, s[22:23]
	v_mul_f32_e32 v187, v31, v227
	v_cvt_pk_bf16_f32 v187, v187, v187
	global_store_short v240, v187, s[22:23] offset:64
	v_mul_f32_e32 v188, v47, v227
	v_cvt_pk_bf16_f32 v188, v188, v188
	global_store_short v240, v188, s[22:23] offset:128
	v_mul_f32_e32 v189, v63, v227
	v_cvt_pk_bf16_f32 v189, v189, v189
	global_store_short v240, v189, s[22:23] offset:192
	v_mul_f32_e32 v190, v79, v227
	v_cvt_pk_bf16_f32 v190, v190, v190
	global_store_short v240, v190, s[22:23] offset:256
	v_mul_f32_e32 v191, v95, v227
	v_cvt_pk_bf16_f32 v191, v191, v191
	global_store_short v240, v191, s[22:23] offset:320
	v_mul_f32_e32 v192, v113, v227
	v_cvt_pk_bf16_f32 v192, v192, v192
	global_store_short v240, v192, s[22:23] offset:384
	v_mul_f32_e32 v193, v129, v227
	v_cvt_pk_bf16_f32 v193, v193, v193
	global_store_short v240, v193, s[22:23] offset:448
	s_waitcnt lgkmcnt(0)
	s_barrier
	s_setprio 0
	s_brev_b32 s30, 64
	v_readlane_b32 s31, v254, 63
	s_movk_i32 s61, 0x1000
	s_mov_b64 s[6:7], 0
